# branch projections: the three branch units of a tile spread over workgroups (write-through running sum, per-tile arrival counter, sc1 loads)
# baseline (speedup 1.0000x reference)
;     DI bool next(int i, Unit& u) const { const int j = i * G + c; if (j >= 3 * 4 * NKSL) return false; u.pm = MMAIN / 256 + j / (4 * NKSL); u.pn = (j / NKSL) & 3; const int kh = j % NKSL; u.z = kh; u.offA = (unsigned)(kh * 512); u.offB = (unsigned)(kh * 512); return true; }
;     __host__ __device__ bool next(int i, Unit& u) const {
;         const long L = (long)i * G + c; if (L >= nwg) return false;
;     DI bool next(int i, Unit& u) const { if (!S.next(i / 3, u)) return false; const int z = i % 3; u.z = z; u.offA = (unsigned)z * (unsigned)(G0ROWS * 512 * 2); u.offB = (unsigned)z * (unsigned)(524288 * 2); return true; }
.LBB0_395:
	s_and_b64 vcc, exec, s[4:5]
	s_cbranch_vccz .LBB0_456
	s_waitcnt vmcnt(0)
	v_mov_b32_e32 v0, v228
	s_cmp_eq_u32 s34, 0
	s_cselect_b32 s0, 35, 32
	v_mov_b32_e32 v0, v228
	s_mov_b32 s1, s92
	s_mov_b32 s2, s82
	s_lshl_b32 s12, s0, 2
	v_mov_b32_e32 v8, v228
	s_mov_b32 s98, 0
	s_cmp_lt_i32 s2, s12
	s_cbranch_scc1 .Lbr_first_done
	s_sub_i32 s2, s2, s12
	s_mov_b32 s98, 1
.Lbr_first_done:
	s_cmp_lt_i32 s2, s12
	s_cselect_b64 s[16:17], -1, 0
	s_cmp_ge_i32 s2, s12
	v_readfirstlane_b32 s33, v8
	s_cbranch_scc1 .LBB0_402
	s_ashr_i32 s3, s2, 31
	s_lshr_b32 s3, s3, 29
	s_add_i32 s3, s2, s3
	s_lshr_b32 s11, s0, 1
	s_and_b32 s4, s3, -8
	s_mov_b64 s[20:21], s[18:19]
	s_and_b32 s18, s12, 4
	s_sub_i32 s6, s2, s4
	s_add_i32 s7, s11, 1
	s_cmp_ge_i32 s6, s18
	s_mov_b64 s[4:5], -1
	s_cbranch_scc0 .LBB0_399
	s_sub_i32 s5, s6, s18
	s_mul_i32 s4, s7, s18
	s_mul_i32 s5, s5, s11
	s_add_i32 s10, s5, s4
	s_mov_b64 s[4:5], 0

; #define PG8_WAIT_V(n) asm volatile("s_waitcnt vmcnt(" #n ")" ::: "memory")
; #define PG8_BAR __builtin_amdgcn_s_barrier()
; template <class Epi, class Sched, bool ALIGN_EPI = false, bool SP2 = false>
; __device__ __forceinline__ void gemm_phase(const int tid, PG8_LAS unsigned char* lds, const Gemm g, const Sched& S, const Epi& E) {
;     const int wid = __builtin_amdgcn_readfirstlane(tid >> 6), lane = tid & 63, wr = wid >> 2, wc = wid & 3, fr = lane & 15, fq = lane >> 4;
;     const int K = g.ld ? g.ld : g.K, nt = g.K / BK;
;     unsigned voffA[2], voffB[2];
; #pragma unroll
;     for (int i = 0; i < 2; ++i) { int R, C; stage_rc(tid * 16 + i * 8192, R, C); const int Rb = Epi::PERM ? ((R & ~31) + perm32(R & 31)) : R;
;         voffA[i] = (unsigned)(R * K + C) * 2u; voffB[i] = (unsigned)(Rb * K + C) * 2u; }
;     const size_t kstep = (size_t)(BK * 2);
;     const size_t hstep = (size_t)HALF * K * 2;
;     const size_t tstep = 2 * hstep;
;     const unsigned ldsw = (unsigned)wid * 1024u;
;     const int aoff = lds_byte(wr * 64 + fr, fq * 8), boff = lds_byte(wc * 32 + fr, fq * 8);
;     ...
;     Unit cur, nxt; int ui = 0;
;     if (!S.next(0, cur)) return;
;     f32x4 acc[2][2][4][2];
; #pragma unroll
;     for (int a = 0; a < 2; ++a)
; #pragma unroll
;         for (int b = 0; b < 2; ++b)
; #pragma unroll
;             for (int m = 0; m < 4; ++m)
; #pragma unroll
;                 for (int n = 0; n < 2; ++n) acc[a][b][m][n] = (f32x4){0.f, 0.f, 0.f, 0.f};
;     bf16x8 At[4][2], B0[2][2], B1[2][2];
;     const char* cA = (const char*)g.A + (size_t)cur.pm * tstep + cur.offA; const char* cB = (const char*)g.Bt + (size_t)cur.pn * tstep + cur.offB;
;     S.a_ready(cur);
;     if constexpr (SP2) {
;         PG8_STAGE(PG8_SB(0, 0), cB, voffB); PG8_STAGE(PG8_SB(0, 1), cB + hstep, voffB); PG8_STAGE(PG8_SA(0, 0), cA, voffA); PG8_STAGE(PG8_SA(0, 1), cA + hstep, voffA);
;         if (wr == 1) PG8_BAR;
;         PG8_WAIT_V(2); PG8_BAR;
;         PG8_STAGE(PG8_SB(1, 0), cB + kstep, voffB); PG8_STAGE(PG8_SA(1, 0), cA + kstep, voffA); PG8_STAGE(PG8_SB(1, 1), cB + hstep + kstep, voffB);
;         PG8_WAIT_V(6); PG8_BAR;
;     } else {
;         PG8_STAGE(PG8_SB(0, 0), cB, voffB); PG8_STAGE(PG8_SA(0, 0), cA, voffA); PG8_STAGE(PG8_SB(0, 1), cB + hstep, voffB); PG8_STAGE(PG8_SA(0, 1), cA + hstep, voffA);
;         if (wr == 1) PG8_BAR;
;         PG8_WAIT_V(4); PG8_BAR;
.LBB0_402:
	s_load_dwordx4 s[4:7], s[18:19], 0xe8
	s_andn2_b64 vcc, exec, s[16:17]
	s_cbranch_vccnz .LBB0_456
	v_ashrrev_i32_e32 v1, 31, v8
	v_lshrrev_b32_e32 v1, 26, v1
	v_add_u32_e32 v1, v8, v1
	v_ashrrev_i32_e32 v9, 6, v1
	v_bfe_i32 v1, v8, 27, 1
	v_lshlrev_b32_e32 v0, 4, v8
	v_lshrrev_b32_e32 v1, 22, v1
	v_add_u32_e32 v1, v0, v1
	v_and_b32_e32 v1, 0xfffffc00, v1
	v_sub_u32_e32 v1, v0, v1
	v_lshrrev_b32_e32 v2, 4, v1
	v_bitop3_b32 v2, v2, v1, 32 bitop3:0x6c
	v_ashrrev_i32_e32 v1, 31, v1
	v_lshrrev_b32_e32 v1, 26, v1
	s_mul_i32 s10, s96, 0x2400000
	v_add_u32_e32 v1, v2, v1
	s_mul_hi_i32 s3, s96, 0x2400000
	s_waitcnt lgkmcnt(0)
	s_add_u32 s11, s6, s10
	v_ashrrev_i32_e32 v10, 6, v1
	s_addc_u32 s16, s7, s3
	v_lshlrev_b32_e32 v3, 3, v9
	v_mul_i32_i24_e32 v4, 64, v10
	s_add_u32 s3, s4, 0x2240000
	v_and_b32_e32 v3, -16, v3
	v_sub_u32_e32 v2, v2, v4
	s_addc_u32 s10, s5, 0
	v_add_u32_e32 v1, v10, v3
	v_lshlrev_b32_e32 v3, 5, v9
	v_ashrrev_i16_sdwa v2, v231, sext(v2) dst_sel:DWORD dst_unused:UNUSED_PAD src0_sel:DWORD src1_sel:BYTE_0
	s_add_u32 s11, s11, 0xd280000
	v_and_b32_e32 v3, 32, v3
	v_bfe_i32 v11, v2, 0, 16
	s_mov_b64 s[94:95], s[18:19]
	s_addc_u32 s18, s16, 0
	v_and_b32_e32 v5, 3, v10
	s_mov_b32 s16, 0x3fffe0
	v_add_lshl_u32 v3, v3, v11, 1
	v_add_u32_e32 v0, 0x2000, v0
	v_lshlrev_b32_e32 v2, 1, v1
	v_lshrrev_b32_e32 v4, 2, v1
	v_and_or_b32 v5, v1, s16, v5
	v_lshl_add_u32 v204, v1, 10, v3
	v_ashrrev_i32_e32 v1, 31, v0
	v_lshrrev_b32_e32 v1, 22, v1
	v_add_u32_e32 v1, v0, v1
	v_ashrrev_i32_e32 v12, 10, v1
	v_mul_i32_i24_e32 v1, 0x400, v12
	v_sub_u32_e32 v0, v0, v1
	v_and_b32_e32 v2, 24, v2
	v_and_b32_e32 v4, 4, v4
	v_lshrrev_b32_e32 v1, 4, v0
	v_or3_b32 v2, v5, v4, v2
	v_bitop3_b32 v0, v1, v0, 32 bitop3:0x6c
	v_lshl_add_u32 v32, v2, 10, v3
	v_ashrrev_i32_e32 v2, 31, v0
	v_lshrrev_b32_e32 v2, 26, v2
	v_lshlrev_b32_e32 v1, 3, v12
	v_add_u32_e32 v2, v0, v2
	v_and_b32_e32 v1, -16, v1
	v_ashrrev_i32_e32 v13, 6, v2
	v_add_u32_e32 v1, v13, v1
	v_and_b32_e32 v2, 0xc0, v2
	v_and_b32_e32 v4, 3, v13
	s_ashr_i32 s41, s33, 6
	s_ashr_i32 s53, s52, 31
	s_ashr_i32 s51, s50, 31
	s_ashr_i32 s40, s33, 8
	v_sub_u32_e32 v0, v0, v2
	v_and_or_b32 v4, v1, s16, v4
	s_lshl_b32 s19, s41, 10
	s_lshl_b64 s[16:17], s[52:53], 18
	s_lshl_b64 s[20:21], s[50:51], 18
	v_ashrrev_i16_sdwa v0, v231, sext(v0) dst_sel:DWORD dst_unused:UNUSED_PAD src0_sel:DWORD src1_sel:BYTE_0
	s_add_u32 s20, s11, s20
	v_lshlrev_b32_e32 v3, 5, v12
	v_bfe_i32 v14, v0, 0, 16
	v_lshlrev_b32_e32 v0, 1, v1
	v_lshrrev_b32_e32 v2, 2, v1
	s_addc_u32 s21, s18, s21
	s_lshl_b32 s99, s98, 20
	s_add_u32 s20, s20, s99
	s_addc_u32 s21, s21, 0
	s_add_i32 s35, s19, 0
	v_and_b32_e32 v3, 32, v3
	v_and_b32_e32 v0, 24, v0
	v_and_b32_e32 v2, 4, v2
	s_add_i32 m0, s35, 0x10000
	v_or3_b32 v0, v4, v2, v0
	v_add_lshl_u32 v2, v3, v14, 1
	global_load_lds_dwordx4 v32, s[20:21]
	s_add_i32 m0, s35, 0x12000
	v_lshl_add_u32 v208, v0, 10, v2
	s_add_u32 s36, s20, 0x20000
	global_load_lds_dwordx4 v208, s[20:21]
	s_addc_u32 s37, s21, 0
	s_add_i32 m0, s35, 0x14000
	v_lshl_add_u32 v206, v1, 10, v2
	global_load_lds_dwordx4 v32, s[36:37]
	s_add_i32 m0, s35, 0x16000
	s_add_u32 s54, s3, s16
	global_load_lds_dwordx4 v208, s[36:37]
	s_addc_u32 s55, s10, s17
	s_mul_i32 s99, s98, 0x8c0000
	s_add_u32 s54, s54, s99
	s_addc_u32 s55, s55, 0
	s_add_i32 s36, s35, 0x2000
	s_mov_b32 m0, s35
	s_add_u32 s16, s54, 0x20000
	global_load_lds_dwordx4 v204, s[54:55]
	s_mov_b32 m0, s36
	s_addc_u32 s17, s55, 0
	s_add_i32 s37, s35, 0x4000
	global_load_lds_dwordx4 v206, s[54:55]
	s_mov_b32 m0, s37
	s_add_i32 s51, s35, 0x6000
	global_load_lds_dwordx4 v204, s[16:17]
	s_mov_b32 m0, s51
	v_writelane_b32 v254, s68, 24
	global_load_lds_dwordx4 v206, s[16:17]
	v_mov_b32_e32 v209, v33
	v_mov_b32_e32 v205, v33
	v_mov_b32_e32 v207, v33
	s_cmp_eq_u32 s40, 1
	v_writelane_b32 v254, s69, 25
	v_lshl_add_u64 v[6:7], s[20:21], 0, v[32:33]
	v_lshl_add_u64 v[4:5], s[20:21], 0, v[208:209]
	v_lshl_add_u64 v[0:1], s[54:55], 0, v[204:205]
	s_cselect_b64 s[16:17], -1, 0
	s_cmp_lg_u32 s40, 1
	v_lshl_add_u64 v[2:3], s[54:55], 0, v[206:207]
	s_cbranch_scc1 .LBB0_405
	s_barrier
.LBB0_405:
	s_add_u32 s53, s6, 0x15cba000
	v_lshrrev_b32_e32 v16, 1, v8
	s_addc_u32 s56, s7, 0
	v_and_b32_e32 v16, 24, v16
	s_add_u32 s38, s4, 0x5f80000
	v_and_b32_e32 v15, 15, v8
	v_lshlrev_b32_e32 v17, 1, v16
	v_lshlrev_b32_e32 v8, 2, v8
	s_addc_u32 s39, s5, 0
	v_lshl_or_b32 v242, s40, 6, v15
	v_lshl_or_b32 v15, v15, 6, v17
	s_lshl_b32 s4, s40, 13
	v_and_b32_e32 v8, 32, v8
	v_bitop3_b32 v17, v15, s4, v8 bitop3:0xde
	s_lshl_b32 s4, s41, 5
	s_and_b32 s6, s4, 0x60
	s_add_i32 m0, s35, 0x18000
	v_lshl_add_u64 v[6:7], v[6:7], 0, s[76:77]
	s_lshl_b32 s4, s6, 7
	s_waitcnt vmcnt(2)
	s_barrier
	global_load_lds_dwordx4 v[6:7], off
	v_lshl_add_u64 v[4:5], v[4:5], 0, s[76:77]
	s_add_i32 m0, s35, 0x1a000
	s_add_i32 s57, s35, 0x8000
	s_add_i32 s58, s35, 0xa000
	v_bitop3_b32 v243, s4, v15, v8 bitop3:0xf6
	global_load_lds_dwordx4 v[4:5], off
	v_lshl_add_u64 v[0:1], v[0:1], 0, s[76:77]
	s_mov_b32 m0, s57
	s_add_u32 s4, s20, 0x20080
	global_load_lds_dwordx4 v[0:1], off
	v_lshl_add_u64 v[0:1], v[2:3], 0, s[76:77]
	s_mov_b32 m0, s58
	s_addc_u32 s5, s21, 0
	global_load_lds_dwordx4 v[0:1], off
	s_add_i32 m0, s35, 0x1c000
	v_lshl_add_u64 v[0:1], s[4:5], 0, v[32:33]
	global_load_lds_dwordx4 v[0:1], off
	v_lshl_add_u64 v[0:1], s[4:5], 0, v[208:209]
	s_add_i32 m0, s35, 0x1e000
	s_cmpk_lt_u32 s33, 0x100
	global_load_lds_dwordx4 v[0:1], off
	v_lshlrev_b32_e32 v0, 13, v9
	v_and_b32_e32 v0, 0xffffc000, v0
	v_lshl_add_u32 v0, v10, 10, v0
	v_and_b32_e32 v1, 1, v9
	v_lshl_or_b32 v0, v1, 6, v0
	v_lshl_add_u32 v210, v11, 1, v0
	v_lshlrev_b32_e32 v0, 13, v12
	v_and_b32_e32 v0, 0xffffc000, v0
	s_waitcnt vmcnt(6)
	v_lshl_add_u32 v0, v13, 10, v0
	v_and_b32_e32 v1, 1, v12
	s_cselect_b64 s[40:41], -1, 0
	s_lshr_b32 s60, s0, 1
	v_lshl_or_b32 v0, v1, 6, v0
	s_mov_b32 s66, s98
	s_ashr_i32 s59, s2, 31
	s_and_b32 s61, s12, 4
	s_add_i32 s62, s60, 1
	v_or_b32_e32 v244, s6, v16
	v_mov_b32_e32 v211, v33
	v_lshl_add_u32 v212, v14, 1, v0
	v_mov_b32_e32 v213, v33
	v_add_u32_e32 v245, 0, v17
	s_mov_b32 s33, 0
	s_mov_b32 s64, 0
	s_mov_b32 s63, 0
	s_mov_b32 s65, s66
	s_barrier
	s_branch .LBB0_408

;     DI bool next(int i, Unit& u) const { const int j = i * G + c; if (j >= 3 * 4 * NKSL) return false; u.pm = MMAIN / 256 + j / (4 * NKSL); u.pn = (j / NKSL) & 3; const int kh = j % NKSL; u.z = kh; u.offA = (unsigned)(kh * 512); u.offB = (unsigned)(kh * 512); return true; }
;     __host__ __device__ bool next(int i, Unit& u) const {
;         const long L = (long)i * G + c; if (L >= nwg) return false;
;         int wgid = (int)L; { const int q = nwg / NXCD, r = nwg % NXCD, xcd = wgid % NXCD, off = wgid / NXCD; wgid = (xcd < r ? xcd * (q + 1) : r * (q + 1) + (xcd - r) * q) + off; }
;         const int nig = WGM * nN, gid = wgid / nig, fm = gid * WGM, gsz = (nM - fm) < WGM ? (nM - fm) : WGM;
;         u.pm = fm + ((wgid % nig) % gsz); u.pn = (wgid % nig) / gsz; return true;
;     DI bool next(int i, Unit& u) const { if (!S.next(i / 3, u)) return false; const int z = i % 3; u.z = z; u.offA = (unsigned)z * (unsigned)(G0ROWS * 512 * 2); u.offB = (unsigned)z * (unsigned)(524288 * 2); return true; }
.LBB0_408:
	s_add_i32 s63, s63, 1
	s_mul_i32 s6, s63, s1
	s_add_i32 s6, s6, s82
	s_mov_b32 s43, 0
	s_cmp_lt_u32 s6, s12
	s_cbranch_scc1 .Lbr_zdone
	s_sub_i32 s6, s6, s12
	s_mov_b32 s43, 1
	s_cmp_lt_u32 s6, s12
	s_cbranch_scc1 .Lbr_zdone
	s_sub_i32 s6, s6, s12
	s_mov_b32 s43, 2
.Lbr_zdone:
	s_cmp_lt_u32 s6, s12
	s_cselect_b64 s[4:5], -1, 0
	s_cselect_b64 vcc, 0, -1
	s_cbranch_vccnz .LBB0_414
	s_ashr_i32 s7, s6, 31
	s_lshr_b32 s7, s7, 29
	s_add_i32 s33, s6, s7
	s_and_b32 s7, s33, -8
	s_sub_i32 s42, s6, s7
	s_cmp_ge_i32 s42, s61
	s_mov_b64 s[6:7], -1
	s_cbranch_scc0 .LBB0_411
	s_sub_i32 s6, s42, s61
	s_mul_i32 s6, s6, s60
	s_mul_i32 s7, s62, s61
	s_add_i32 s44, s6, s7
	s_mov_b64 s[6:7], 0

;     DI bool next(int i, Unit& u) const { const int j = i * G + c; if (j >= 3 * 4 * NKSL) return false; u.pm = MMAIN / 256 + j / (4 * NKSL); u.pn = (j / NKSL) & 3; const int kh = j % NKSL; u.z = kh; u.offA = (unsigned)(kh * 512); u.offB = (unsigned)(kh * 512); return true; }
;     __host__ __device__ bool next(int i, Unit& u) const {
;     ...
;         int wgid = (int)L; { const int q = nwg / NXCD, r = nwg % NXCD, xcd = wgid % NXCD, off = wgid / NXCD; wgid = (xcd < r ? xcd * (q + 1) : r * (q + 1) + (xcd - r) * q) + off; }
;         const int nig = WGM * nN, gid = wgid / nig, fm = gid * WGM, gsz = (nM - fm) < WGM ? (nM - fm) : WGM;
;         u.pm = fm + ((wgid % nig) % gsz); u.pn = (wgid % nig) / gsz; return true;
;     DI bool next(int i, Unit& u) const { if (!S.next(i / 3, u)) return false; const int z = i % 3; u.z = z; u.offA = (unsigned)z * (unsigned)(G0ROWS * 512 * 2); u.offB = (unsigned)z * (unsigned)(524288 * 2); return true; }
.LBB0_413:
	s_ashr_i32 s6, s33, 3
	s_add_i32 s6, s44, s6
	s_ashr_i32 s7, s6, 31
	s_lshr_b32 s7, s7, 27
	s_add_i32 s7, s6, s7
	s_ashr_i32 s33, s7, 5
	s_lshl_b32 s33, s33, 3
	s_sub_i32 s42, s0, s33
	s_min_i32 s44, s42, 8
	s_abs_i32 s42, s44
	v_cvt_f32_u32_e32 v0, s42
	s_sub_i32 s46, 0, s42
	s_andn2_b32 s7, s7, 31
	s_sub_i32 s6, s6, s7
	v_rcp_iflag_f32_e32 v0, v0
	s_abs_i32 s7, s6
	s_xor_b32 s45, s6, s44
	s_ashr_i32 s45, s45, 31
	v_mul_f32_e32 v0, 0x4f7ffffe, v0
	v_cvt_u32_f32_e32 v0, v0
	s_nop 0
	v_readfirstlane_b32 s47, v0
	s_mul_i32 s46, s46, s47
	s_mul_hi_u32 s46, s47, s46
	s_add_i32 s47, s47, s46
	s_mul_hi_u32 s46, s7, s47
	s_mul_i32 s47, s46, s42
	s_sub_i32 s7, s7, s47
	s_add_i32 s48, s46, 1
	s_sub_i32 s47, s7, s42
	s_cmp_ge_u32 s7, s42
	s_cselect_b32 s46, s48, s46
	s_cselect_b32 s7, s47, s7
	s_add_i32 s47, s46, 1
	s_cmp_ge_u32 s7, s42
	s_cselect_b32 s7, s47, s46
	s_xor_b32 s7, s7, s45
	s_sub_i32 s42, s7, s45
	s_mul_i32 s7, s42, s44
	s_sub_i32 s6, s6, s7
	s_mov_b32 s65, s43
	s_add_i32 s44, s33, s6
	s_mul_i32 s64, s65, 0x8c0000
	s_lshl_b32 s33, s65, 20

;     DI void operator()(const f32x4 (&acc)[2][2][4][2], const Unit& u, int wr, int wc, int fr, int fq) const {
;         const int mode = u.z; const bf16_t* zg = zg0 + mode * 1024;
;         const int rowb = u.pm * 256 + wr * 64 + fr, colb = u.pn * 256 + wc * 32 + 8 * fq;
; #pragma unroll
;         for (int ai = 0; ai < 2; ++ai) {
;             u32x4 zr[4][2], mr[4][2];
; #pragma unroll
;             for (int m = 0; m < 4; ++m)
; #pragma unroll
;                 for (int bj = 0; bj < 2; ++bj) { const int row = rowb + ai * 128 + m * 16, col = colb + bj * 128;
;                     zr[m][bj] = *(const u32x4*)(zg + (size_t)row * 3072 + col);
;                     if (mode != 0) mr[m][bj] = *(const u32x4*)(mixb + (size_t)row * 1024 + col); else mr[m][bj] = (u32x4){0u, 0u, 0u, 0u}; }
.LBB0_418:
	s_load_dwordx2 s[100:101], s[86:87], 0xf0
	s_lshl_b32 s6, s52, 2
	s_add_i32 s6, s6, s50
	s_lshl_b32 s6, s6, 4
	s_add_i32 s6, s6, 0x11259600
	s_waitcnt lgkmcnt(0)
	s_add_u32 s100, s100, s6
	s_addc_u32 s101, s101, 0
	s_lshl_b32 s6, s96, 2
	s_add_i32 s6, s6, s34
	s_cmp_lt_u32 s52, 32
	s_cselect_b32 s6, s6, s96
	s_lshl_b32 s6, s6, 4
	s_lshl_b32 s7, s66, 3
	s_add_i32 s6, s6, s7
	s_cmp_eq_u32 s66, 0
	s_cbranch_scc1 .Lbr_polled
	s_mov_b32 s99, 0
.Lbr_poll:
	global_load_dword v130, v33, s[100:101] sc1
	s_waitcnt vmcnt(0)
	v_readfirstlane_b32 s7, v130
	s_cmp_ge_u32 s7, s6
	s_cbranch_scc1 .Lbr_acq
	s_sleep 2
	s_add_i32 s99, s99, 1
	s_cmp_lt_u32 s99, 0x2000
	s_cbranch_scc1 .Lbr_poll
.Lbr_acq:
.Lbr_polled:
	s_lshl_b32 s6, s66, 11
	s_add_u32 s54, s53, s6
	s_addc_u32 s55, s56, 0
	v_lshl_add_u32 v216, s52, 8, v242
	v_lshl_or_b32 v214, s50, 8, v244
	v_mov_b64_e32 v[130:131], s[54:55]
	v_mad_i64_i32 v[130:131], s[6:7], v216, s25, v[130:131]
	v_ashrrev_i32_e32 v215, 31, v214
	v_lshl_add_u64 v[132:133], v[214:215], 1, v[130:131]
	global_load_dwordx4 v[188:191], v[132:133], off
	v_ashrrev_i32_e32 v217, 31, v216
	v_lshlrev_b64 v[130:131], 11, v[216:217]
	s_cmp_lg_u32 s66, 0
	v_lshl_add_u64 v[224:225], s[38:39], 0, v[130:131]
	s_cselect_b64 s[20:21], -1, 0
	s_cmp_eq_u32 s66, 0
	v_lshl_add_u64 v[130:131], v[214:215], 1, v[224:225]
	s_cbranch_scc1 .LBB0_420
	global_load_dwordx4 v[192:195], v[130:131], off sc1
	s_branch .LBB0_421

; DI u32x4 pack8(f32x4 a, f32x4 b) { u32x4 w; w.x = cvt_pk_bf16(a[0], a[1]); w.y = cvt_pk_bf16(a[2], a[3]); w.z = cvt_pk_bf16(b[0], b[1]); w.w = cvt_pk_bf16(b[2], b[3]); return w; }
;     DI void operator()(const f32x4 (&acc)[2][2][4][2], const Unit& u, int wr, int wc, int fr, int fq) const {
;     ...
;         for (int ai = 0; ai < 2; ++ai) {
;             u32x4 zr[4][2], mr[4][2];
; #pragma unroll
;             for (int m = 0; m < 4; ++m)
; #pragma unroll
;                 for (int bj = 0; bj < 2; ++bj) { const int row = rowb + ai * 128 + m * 16, col = colb + bj * 128;
;                     zr[m][bj] = *(const u32x4*)(zg + (size_t)row * 3072 + col);
;                     if (mode != 0) mr[m][bj] = *(const u32x4*)(mixb + (size_t)row * 1024 + col); else mr[m][bj] = (u32x4){0u, 0u, 0u, 0u}; }
; #pragma unroll
;             for (int m = 0; m < 4; ++m)
; #pragma unroll
;                 for (int bj = 0; bj < 2; ++bj) { const int row = rowb + ai * 128 + m * 16, col = colb + bj * 128;
;                     f32x4 z0, z1, p0, p1; unpack8(zr[m][bj], z0, z1); unpack8(mr[m][bj], p0, p1);
;                     const f32x4 v0 = acc[ai][bj][m][0] * z0 + p0, v1 = acc[ai][bj][m][1] * z1 + p1;
;                     *(u32x4*)(mixb + (size_t)row * 1024 + col) = pack8(v0, v1); }
.LBB0_421:
	global_load_dwordx4 v[184:187], v[132:133], off offset:256
	v_cndmask_b32_e64 v132, 0, 1, s[20:21]
	v_mov_b32_e32 v160, 0
	v_cmp_ne_u32_e64 s[6:7], 1, v132
	s_andn2_b64 vcc, exec, s[20:21]
	v_mov_b32_e32 v180, 0
	v_mov_b32_e32 v181, 0
	v_mov_b32_e32 v182, 0
	v_mov_b32_e32 v183, 0
	s_cbranch_vccnz .LBB0_423
	global_load_dwordx4 v[180:183], v[130:131], off offset:256 sc1
.LBB0_423:
	v_or_b32_e32 v130, 16, v216
	v_mov_b64_e32 v[132:133], s[54:55]
	v_mad_i64_i32 v[132:133], s[20:21], v130, s25, v[132:133]
	v_lshl_add_u64 v[132:133], v[214:215], 1, v[132:133]
	global_load_dwordx4 v[176:179], v[132:133], off
	v_ashrrev_i32_e32 v131, 31, v130
	v_lshlrev_b64 v[130:131], 11, v[130:131]
	v_lshl_add_u64 v[222:223], s[38:39], 0, v[130:131]
	s_and_b64 vcc, exec, s[6:7]
	v_lshl_add_u64 v[130:131], v[214:215], 1, v[222:223]
	v_mov_b32_e32 v161, 0
	v_mov_b32_e32 v162, 0
	v_mov_b32_e32 v163, 0
	s_cbranch_vccnz .LBB0_425
	global_load_dwordx4 v[160:163], v[130:131], off sc1
.LBB0_425:
	global_load_dwordx4 v[172:175], v[132:133], off offset:256
	v_mov_b32_e32 v148, 0
	s_and_b64 vcc, exec, s[6:7]
	v_mov_b32_e32 v168, 0
	v_mov_b32_e32 v169, 0
	v_mov_b32_e32 v170, 0
	v_mov_b32_e32 v171, 0
	s_cbranch_vccnz .LBB0_427
	global_load_dwordx4 v[168:171], v[130:131], off offset:256 sc1
.LBB0_427:
	v_or_b32_e32 v130, 32, v216
	v_mov_b64_e32 v[132:133], s[54:55]
	v_mad_i64_i32 v[132:133], s[20:21], v130, s25, v[132:133]
	v_lshl_add_u64 v[132:133], v[214:215], 1, v[132:133]
	global_load_dwordx4 v[164:167], v[132:133], off
	v_ashrrev_i32_e32 v131, 31, v130
	v_lshlrev_b64 v[130:131], 11, v[130:131]
	v_lshl_add_u64 v[220:221], s[38:39], 0, v[130:131]
	s_and_b64 vcc, exec, s[6:7]
	v_lshl_add_u64 v[130:131], v[214:215], 1, v[220:221]
	v_mov_b32_e32 v149, 0
	v_mov_b32_e32 v150, 0
	v_mov_b32_e32 v151, 0
	s_cbranch_vccnz .LBB0_429
	global_load_dwordx4 v[148:151], v[130:131], off sc1
.LBB0_429:
	global_load_dwordx4 v[156:159], v[132:133], off offset:256
	v_mov_b32_e32 v132, 0
	s_and_b64 vcc, exec, s[6:7]
	v_mov_b32_e32 v152, 0
	v_mov_b32_e32 v153, 0
	v_mov_b32_e32 v154, 0
	v_mov_b32_e32 v155, 0
	s_cbranch_vccnz .LBB0_431
	global_load_dwordx4 v[152:155], v[130:131], off offset:256 sc1
.LBB0_431:
	v_or_b32_e32 v134, 48, v216
	v_mov_b64_e32 v[130:131], s[54:55]
	v_mad_i64_i32 v[130:131], s[20:21], v134, s25, v[130:131]
	v_lshl_add_u64 v[130:131], v[214:215], 1, v[130:131]
	global_load_dwordx4 v[144:147], v[130:131], off
	v_ashrrev_i32_e32 v135, 31, v134
	v_lshlrev_b64 v[134:135], 11, v[134:135]
	v_lshl_add_u64 v[218:219], s[38:39], 0, v[134:135]
	s_and_b64 vcc, exec, s[6:7]
	v_lshl_add_u64 v[226:227], v[214:215], 1, v[218:219]
	v_mov_b32_e32 v133, 0
	v_mov_b32_e32 v134, 0
	v_mov_b32_e32 v135, 0
	s_cbranch_vccnz .LBB0_433
	global_load_dwordx4 v[132:135], v[226:227], off sc1
.LBB0_433:
	global_load_dwordx4 v[140:143], v[130:131], off offset:256
	v_mov_b32_e32 v130, 0
	s_and_b64 vcc, exec, s[6:7]
	v_mov_b32_e32 v136, 0
	v_mov_b32_e32 v137, 0
	v_mov_b32_e32 v138, 0
	v_mov_b32_e32 v139, 0
	s_cbranch_vccnz .LBB0_435
	global_load_dwordx4 v[136:139], v[226:227], off offset:256 sc1
.LBB0_435:
	s_waitcnt vmcnt(0)
	v_lshlrev_b32_e32 v226, 16, v188
	v_and_b32_e32 v227, 0xffff0000, v188
	v_lshlrev_b32_e32 v248, 16, v192
	v_and_b32_e32 v249, 0xffff0000, v192
	v_lshlrev_b32_e32 v188, 16, v189
	v_and_b32_e32 v189, 0xffff0000, v189
	v_lshlrev_b32_e32 v246, 16, v190
	v_and_b32_e32 v247, 0xffff0000, v190
	v_lshlrev_b32_e32 v190, 16, v191
	v_and_b32_e32 v191, 0xffff0000, v191
	v_lshlrev_b32_e32 v192, 16, v193
	v_and_b32_e32 v193, 0xffff0000, v193
	v_lshlrev_b32_e32 v250, 16, v194
	v_and_b32_e32 v251, 0xffff0000, v194
	v_lshlrev_b32_e32 v194, 16, v195
	v_and_b32_e32 v195, 0xffff0000, v195
	v_pk_fma_f32 v[126:127], v[126:127], v[226:227], v[248:249]
	v_pk_fma_f32 v[128:129], v[128:129], v[188:189], v[192:193]
	v_pk_fma_f32 v[188:189], v[124:125], v[190:191], v[194:195]
	v_pk_fma_f32 v[124:125], v[122:123], v[246:247], v[250:251]
	v_cvt_pk_bf16_f32 v122, v126, v127
	v_lshlrev_b64 v[126:127], 1, v[214:215]
	v_cvt_pk_bf16_f32 v123, v128, v129
	v_cvt_pk_bf16_f32 v124, v124, v125
	v_cvt_pk_bf16_f32 v125, v188, v189
	v_lshl_add_u64 v[128:129], v[224:225], 0, v[126:127]
	global_store_dwordx4 v[128:129], v[122:125], off sc1
	v_lshlrev_b32_e32 v188, 16, v180
	v_and_b32_e32 v189, 0xffff0000, v180
	v_lshlrev_b32_e32 v122, 16, v184
	v_and_b32_e32 v123, 0xffff0000, v184
	v_lshlrev_b32_e32 v124, 16, v185
	v_and_b32_e32 v125, 0xffff0000, v185
	v_lshlrev_b32_e32 v184, 16, v186
	v_and_b32_e32 v185, 0xffff0000, v186
	v_lshlrev_b32_e32 v186, 16, v187
	v_and_b32_e32 v187, 0xffff0000, v187
	v_lshlrev_b32_e32 v180, 16, v181
	v_and_b32_e32 v181, 0xffff0000, v181
	v_lshlrev_b32_e32 v190, 16, v182
	v_and_b32_e32 v191, 0xffff0000, v182
	v_lshlrev_b32_e32 v182, 16, v183
	v_and_b32_e32 v183, 0xffff0000, v183
	v_pk_fma_f32 v[120:121], v[120:121], v[124:125], v[180:181]
	v_pk_fma_f32 v[118:119], v[118:119], v[122:123], v[188:189]
	v_pk_fma_f32 v[122:123], v[116:117], v[186:187], v[182:183]
	v_pk_fma_f32 v[116:117], v[114:115], v[184:185], v[190:191]
	v_cvt_pk_bf16_f32 v114, v118, v119
	v_cvt_pk_bf16_f32 v115, v120, v121
	v_cvt_pk_bf16_f32 v116, v116, v117
	v_cvt_pk_bf16_f32 v117, v122, v123
	global_store_dwordx4 v[128:129], v[114:117], off offset:256 sc1
	v_lshlrev_b32_e32 v118, 16, v178
	v_and_b32_e32 v119, 0xffff0000, v178
	v_lshlrev_b32_e32 v114, 16, v176
	v_and_b32_e32 v115, 0xffff0000, v176
	v_lshlrev_b32_e32 v116, 16, v177
	v_and_b32_e32 v117, 0xffff0000, v177
	v_lshlrev_b32_e32 v120, 16, v179
	v_and_b32_e32 v121, 0xffff0000, v179
	v_lshlrev_b32_e32 v122, 16, v160
	v_and_b32_e32 v123, 0xffff0000, v160
; DI u32x4 pack8(f32x4 a, f32x4 b) { u32x4 w; w.x = cvt_pk_bf16(a[0], a[1]); w.y = cvt_pk_bf16(a[2], a[3]); w.z = cvt_pk_bf16(b[0], b[1]); w.w = cvt_pk_bf16(b[2], b[3]); return w; }
;     DI void operator()(const f32x4 (&acc)[2][2][4][2], const Unit& u, int wr, int wc, int fr, int fq) const {
;     ...
;         for (int ai = 0; ai < 2; ++ai) {
;             u32x4 zr[4][2], mr[4][2];
; #pragma unroll
;             for (int m = 0; m < 4; ++m)
; #pragma unroll
;                 for (int bj = 0; bj < 2; ++bj) { const int row = rowb + ai * 128 + m * 16, col = colb + bj * 128;
;                     zr[m][bj] = *(const u32x4*)(zg + (size_t)row * 3072 + col);
;                     if (mode != 0) mr[m][bj] = *(const u32x4*)(mixb + (size_t)row * 1024 + col); else mr[m][bj] = (u32x4){0u, 0u, 0u, 0u}; }
; #pragma unroll
;             for (int m = 0; m < 4; ++m)
; #pragma unroll
;                 for (int bj = 0; bj < 2; ++bj) { const int row = rowb + ai * 128 + m * 16, col = colb + bj * 128;
;                     f32x4 z0, z1, p0, p1; unpack8(zr[m][bj], z0, z1); unpack8(mr[m][bj], p0, p1);
;                     const f32x4 v0 = acc[ai][bj][m][0] * z0 + p0, v1 = acc[ai][bj][m][1] * z1 + p1;
;                     *(u32x4*)(mixb + (size_t)row * 1024 + col) = pack8(v0, v1); }
	v_lshlrev_b32_e32 v124, 16, v161
	v_and_b32_e32 v125, 0xffff0000, v161
	v_lshlrev_b32_e32 v128, 16, v162
	v_and_b32_e32 v129, 0xffff0000, v162
	v_lshlrev_b32_e32 v160, 16, v163
	v_and_b32_e32 v161, 0xffff0000, v163
	v_pk_fma_f32 v[112:113], v[112:113], v[116:117], v[124:125]
	v_pk_fma_f32 v[110:111], v[110:111], v[114:115], v[122:123]
	v_pk_fma_f32 v[114:115], v[108:109], v[120:121], v[160:161]
	v_pk_fma_f32 v[108:109], v[106:107], v[118:119], v[128:129]
	v_cvt_pk_bf16_f32 v106, v110, v111
	v_cvt_pk_bf16_f32 v107, v112, v113
	v_cvt_pk_bf16_f32 v108, v108, v109
	v_cvt_pk_bf16_f32 v109, v114, v115
	v_lshl_add_u64 v[110:111], v[222:223], 0, v[126:127]
	global_store_dwordx4 v[110:111], v[106:109], off sc1
	v_lshlrev_b32_e32 v112, 16, v174
	v_and_b32_e32 v113, 0xffff0000, v174
	v_lshlrev_b32_e32 v106, 16, v172
	v_and_b32_e32 v107, 0xffff0000, v172
	v_lshlrev_b32_e32 v108, 16, v173
	v_and_b32_e32 v109, 0xffff0000, v173
	v_lshlrev_b32_e32 v114, 16, v175
	v_and_b32_e32 v115, 0xffff0000, v175
	v_lshlrev_b32_e32 v116, 16, v168
	v_and_b32_e32 v117, 0xffff0000, v168
	v_lshlrev_b32_e32 v118, 16, v169
	v_and_b32_e32 v119, 0xffff0000, v169
	v_lshlrev_b32_e32 v120, 16, v170
	v_and_b32_e32 v121, 0xffff0000, v170
	v_lshlrev_b32_e32 v122, 16, v171
	v_and_b32_e32 v123, 0xffff0000, v171
	v_pk_fma_f32 v[104:105], v[104:105], v[108:109], v[118:119]
	v_pk_fma_f32 v[102:103], v[102:103], v[106:107], v[116:117]
	v_pk_fma_f32 v[106:107], v[100:101], v[114:115], v[122:123]
	v_pk_fma_f32 v[100:101], v[98:99], v[112:113], v[120:121]
	v_cvt_pk_bf16_f32 v98, v102, v103
	v_cvt_pk_bf16_f32 v99, v104, v105
	v_cvt_pk_bf16_f32 v100, v100, v101
	v_cvt_pk_bf16_f32 v101, v106, v107
	global_store_dwordx4 v[110:111], v[98:101], off offset:256 sc1
	v_lshlrev_b32_e32 v102, 16, v166
	v_and_b32_e32 v103, 0xffff0000, v166
	v_lshlrev_b32_e32 v98, 16, v164
	v_and_b32_e32 v99, 0xffff0000, v164
	v_lshlrev_b32_e32 v100, 16, v165
	v_and_b32_e32 v101, 0xffff0000, v165
	v_lshlrev_b32_e32 v104, 16, v167
	v_and_b32_e32 v105, 0xffff0000, v167
	v_lshlrev_b32_e32 v106, 16, v148
	v_and_b32_e32 v107, 0xffff0000, v148
	v_lshlrev_b32_e32 v108, 16, v149
	v_and_b32_e32 v109, 0xffff0000, v149
	v_lshlrev_b32_e32 v110, 16, v150
	v_and_b32_e32 v111, 0xffff0000, v150
	v_lshlrev_b32_e32 v112, 16, v151
	v_and_b32_e32 v113, 0xffff0000, v151
	v_pk_fma_f32 v[96:97], v[96:97], v[100:101], v[108:109]
	v_pk_fma_f32 v[94:95], v[94:95], v[98:99], v[106:107]
	v_pk_fma_f32 v[98:99], v[92:93], v[104:105], v[112:113]
	v_pk_fma_f32 v[92:93], v[90:91], v[102:103], v[110:111]
	v_cvt_pk_bf16_f32 v90, v94, v95
	v_cvt_pk_bf16_f32 v91, v96, v97
	v_cvt_pk_bf16_f32 v92, v92, v93
	v_cvt_pk_bf16_f32 v93, v98, v99
	v_lshl_add_u64 v[94:95], v[220:221], 0, v[126:127]
	global_store_dwordx4 v[94:95], v[90:93], off sc1
	v_lshlrev_b32_e32 v96, 16, v158
	v_and_b32_e32 v97, 0xffff0000, v158
	v_lshlrev_b32_e32 v90, 16, v156
	v_and_b32_e32 v91, 0xffff0000, v156
	v_lshlrev_b32_e32 v92, 16, v157
	v_and_b32_e32 v93, 0xffff0000, v157
	v_lshlrev_b32_e32 v98, 16, v159
	v_and_b32_e32 v99, 0xffff0000, v159
	v_lshlrev_b32_e32 v100, 16, v152
	v_and_b32_e32 v101, 0xffff0000, v152
	v_lshlrev_b32_e32 v102, 16, v153
	v_and_b32_e32 v103, 0xffff0000, v153
	v_lshlrev_b32_e32 v104, 16, v154
	v_and_b32_e32 v105, 0xffff0000, v154
	v_lshlrev_b32_e32 v106, 16, v155
	v_and_b32_e32 v107, 0xffff0000, v155
	v_pk_fma_f32 v[88:89], v[88:89], v[92:93], v[102:103]
	v_pk_fma_f32 v[86:87], v[86:87], v[90:91], v[100:101]
	v_pk_fma_f32 v[90:91], v[84:85], v[98:99], v[106:107]
	v_pk_fma_f32 v[84:85], v[82:83], v[96:97], v[104:105]
	v_cvt_pk_bf16_f32 v82, v86, v87
	v_cvt_pk_bf16_f32 v83, v88, v89
	v_cvt_pk_bf16_f32 v84, v84, v85
	v_cvt_pk_bf16_f32 v85, v90, v91
	global_store_dwordx4 v[94:95], v[82:85], off offset:256 sc1
	v_lshlrev_b32_e32 v86, 16, v146
	v_and_b32_e32 v87, 0xffff0000, v146
	v_lshlrev_b32_e32 v82, 16, v144
	v_and_b32_e32 v83, 0xffff0000, v144
	v_lshlrev_b32_e32 v84, 16, v145
	v_and_b32_e32 v85, 0xffff0000, v145
	v_lshlrev_b32_e32 v88, 16, v147
	v_and_b32_e32 v89, 0xffff0000, v147
	v_lshlrev_b32_e32 v90, 16, v132
	v_and_b32_e32 v91, 0xffff0000, v132
	v_lshlrev_b32_e32 v92, 16, v133
	v_and_b32_e32 v93, 0xffff0000, v133
	v_lshlrev_b32_e32 v94, 16, v134
	v_and_b32_e32 v95, 0xffff0000, v134
	v_lshlrev_b32_e32 v96, 16, v135
	v_and_b32_e32 v97, 0xffff0000, v135
	v_pk_fma_f32 v[80:81], v[80:81], v[84:85], v[92:93]
	v_pk_fma_f32 v[78:79], v[78:79], v[82:83], v[90:91]
	v_pk_fma_f32 v[82:83], v[76:77], v[88:89], v[96:97]
	v_pk_fma_f32 v[76:77], v[74:75], v[86:87], v[94:95]
	v_cvt_pk_bf16_f32 v74, v78, v79
	v_cvt_pk_bf16_f32 v75, v80, v81
	v_cvt_pk_bf16_f32 v76, v76, v77
	v_cvt_pk_bf16_f32 v77, v82, v83
	v_lshl_add_u64 v[78:79], v[218:219], 0, v[126:127]
	global_store_dwordx4 v[78:79], v[74:77], off sc1
	v_lshlrev_b32_e32 v80, 16, v142
	v_and_b32_e32 v81, 0xffff0000, v142
	v_lshlrev_b32_e32 v74, 16, v140
	v_and_b32_e32 v75, 0xffff0000, v140
	v_lshlrev_b32_e32 v76, 16, v141
	v_and_b32_e32 v77, 0xffff0000, v141
	v_lshlrev_b32_e32 v82, 16, v143
	v_and_b32_e32 v83, 0xffff0000, v143
	v_lshlrev_b32_e32 v84, 16, v136
	v_and_b32_e32 v85, 0xffff0000, v136
	v_lshlrev_b32_e32 v86, 16, v137
	v_and_b32_e32 v87, 0xffff0000, v137
	v_lshlrev_b32_e32 v88, 16, v138
	v_and_b32_e32 v89, 0xffff0000, v138
	v_lshlrev_b32_e32 v90, 16, v139
	v_and_b32_e32 v91, 0xffff0000, v139
	v_pk_fma_f32 v[72:73], v[72:73], v[76:77], v[86:87]
	v_pk_fma_f32 v[70:71], v[70:71], v[74:75], v[84:85]
	v_pk_fma_f32 v[74:75], v[68:69], v[82:83], v[90:91]
	v_pk_fma_f32 v[68:69], v[66:67], v[80:81], v[88:89]
	v_cvt_pk_bf16_f32 v66, v70, v71
	v_cvt_pk_bf16_f32 v67, v72, v73
	v_cvt_pk_bf16_f32 v68, v68, v69
	v_cvt_pk_bf16_f32 v69, v74, v75
	global_store_dwordx4 v[78:79], v[66:69], off offset:256 sc1
	s_and_b64 vcc, exec, s[6:7]
	v_mov_b32_e32 v131, 0
	v_add_u32_e32 v66, 0x80, v216
	v_mov_b64_e32 v[68:69], s[54:55]
	v_mad_i64_i32 v[68:69], s[20:21], v66, s25, v[68:69]
	v_lshl_add_u64 v[68:69], v[68:69], 0, v[126:127]
	global_load_dwordx4 v[122:125], v[68:69], off
	v_ashrrev_i32_e32 v67, 31, v66
	v_lshlrev_b64 v[66:67], 11, v[66:67]
	v_lshl_add_u64 v[138:139], s[38:39], 0, v[66:67]
	v_lshl_add_u64 v[66:67], v[214:215], 1, v[138:139]
	v_mov_b32_e32 v132, 0
	v_mov_b32_e32 v133, 0
	s_cbranch_vccnz .LBB0_437
	global_load_dwordx4 v[130:133], v[66:67], off sc1
;     DI void operator()(const f32x4 (&acc)[2][2][4][2], const Unit& u, int wr, int wc, int fr, int fq) const {
;     ...
;         for (int ai = 0; ai < 2; ++ai) {
;             u32x4 zr[4][2], mr[4][2];
; #pragma unroll
;             for (int m = 0; m < 4; ++m)
; #pragma unroll
;                 for (int bj = 0; bj < 2; ++bj) { const int row = rowb + ai * 128 + m * 16, col = colb + bj * 128;
;                     zr[m][bj] = *(const u32x4*)(zg + (size_t)row * 3072 + col);
;                     if (mode != 0) mr[m][bj] = *(const u32x4*)(mixb + (size_t)row * 1024 + col); else mr[m][bj] = (u32x4){0u, 0u, 0u, 0u}; }
.LBB0_437:
	global_load_dwordx4 v[118:121], v[68:69], off offset:256
	v_mov_b32_e32 v98, 0
	s_and_b64 vcc, exec, s[6:7]
	v_mov_b32_e32 v114, 0
	v_mov_b32_e32 v115, 0
	v_mov_b32_e32 v116, 0
	v_mov_b32_e32 v117, 0
	s_cbranch_vccnz .LBB0_439
	global_load_dwordx4 v[114:117], v[66:67], off offset:256 sc1
.LBB0_439:
	v_add_u32_e32 v66, 0x90, v216
	v_mov_b64_e32 v[68:69], s[54:55]
	v_mad_i64_i32 v[68:69], s[20:21], v66, s25, v[68:69]
	v_lshl_add_u64 v[68:69], v[214:215], 1, v[68:69]
	global_load_dwordx4 v[110:113], v[68:69], off
	v_ashrrev_i32_e32 v67, 31, v66
	v_lshlrev_b64 v[66:67], 11, v[66:67]
	v_lshl_add_u64 v[136:137], s[38:39], 0, v[66:67]
	s_and_b64 vcc, exec, s[6:7]
	v_lshl_add_u64 v[66:67], v[214:215], 1, v[136:137]
	v_mov_b32_e32 v99, 0
	v_mov_b32_e32 v100, 0
	v_mov_b32_e32 v101, 0
	s_cbranch_vccnz .LBB0_441
	global_load_dwordx4 v[98:101], v[66:67], off sc1
.LBB0_441:
	global_load_dwordx4 v[106:109], v[68:69], off offset:256
	v_mov_b32_e32 v82, 0
	s_and_b64 vcc, exec, s[6:7]
	v_mov_b32_e32 v102, 0
	v_mov_b32_e32 v103, 0
	v_mov_b32_e32 v104, 0
	v_mov_b32_e32 v105, 0
	s_cbranch_vccnz .LBB0_443
	global_load_dwordx4 v[102:105], v[66:67], off offset:256 sc1
.LBB0_443:
	v_add_u32_e32 v68, 0xa0, v216
	v_mov_b64_e32 v[66:67], s[54:55]
	v_mad_i64_i32 v[66:67], s[20:21], v68, s25, v[66:67]
	v_lshl_add_u64 v[66:67], v[214:215], 1, v[66:67]
	global_load_dwordx4 v[94:97], v[66:67], off
	v_ashrrev_i32_e32 v69, 31, v68
	v_lshlrev_b64 v[68:69], 11, v[68:69]
	v_lshl_add_u64 v[134:135], s[38:39], 0, v[68:69]
	s_and_b64 vcc, exec, s[6:7]
	v_lshl_add_u64 v[68:69], v[214:215], 1, v[134:135]
	v_mov_b32_e32 v83, 0
	v_mov_b32_e32 v84, 0
	v_mov_b32_e32 v85, 0
	s_cbranch_vccnz .LBB0_445
	global_load_dwordx4 v[82:85], v[68:69], off sc1
.LBB0_445:
	global_load_dwordx4 v[90:93], v[66:67], off offset:256
	v_mov_b32_e32 v66, 0
	s_and_b64 vcc, exec, s[6:7]
	v_mov_b32_e32 v86, 0
	v_mov_b32_e32 v87, 0
	v_mov_b32_e32 v88, 0
	v_mov_b32_e32 v89, 0
	s_cbranch_vccnz .LBB0_447
	global_load_dwordx4 v[86:89], v[68:69], off offset:256 sc1
.LBB0_447:
	v_add_u32_e32 v68, 0xb0, v216
	v_mov_b64_e32 v[70:71], s[54:55]
	v_mad_i64_i32 v[70:71], s[20:21], v68, s25, v[70:71]
	v_lshl_add_u64 v[70:71], v[214:215], 1, v[70:71]
	global_load_dwordx4 v[78:81], v[70:71], off
	v_ashrrev_i32_e32 v69, 31, v68
	v_lshlrev_b64 v[68:69], 11, v[68:69]
	v_lshl_add_u64 v[128:129], s[38:39], 0, v[68:69]
	s_and_b64 vcc, exec, s[6:7]
	v_lshl_add_u64 v[72:73], v[214:215], 1, v[128:129]
	v_mov_b32_e32 v67, 0
	v_mov_b32_e32 v68, 0
	v_mov_b32_e32 v69, 0
	s_cbranch_vccnz .LBB0_449
	global_load_dwordx4 v[66:69], v[72:73], off sc1
.LBB0_449:
	global_load_dwordx4 v[74:77], v[70:71], off offset:256
	s_and_b64 vcc, exec, s[6:7]
	s_cbranch_vccnz .LBB0_451
	global_load_dwordx4 v[70:73], v[72:73], off offset:256 sc1
	s_branch .LBB0_452

; DI u32x4 pack8(f32x4 a, f32x4 b) { u32x4 w; w.x = cvt_pk_bf16(a[0], a[1]); w.y = cvt_pk_bf16(a[2], a[3]); w.z = cvt_pk_bf16(b[0], b[1]); w.w = cvt_pk_bf16(b[2], b[3]); return w; }
;     DI void operator()(const f32x4 (&acc)[2][2][4][2], const Unit& u, int wr, int wc, int fr, int fq) const {
;     ...
;             for (int m = 0; m < 4; ++m)
; #pragma unroll
;                 for (int bj = 0; bj < 2; ++bj) { const int row = rowb + ai * 128 + m * 16, col = colb + bj * 128;
;                     f32x4 z0, z1, p0, p1; unpack8(zr[m][bj], z0, z1); unpack8(mr[m][bj], p0, p1);
;                     const f32x4 v0 = acc[ai][bj][m][0] * z0 + p0, v1 = acc[ai][bj][m][1] * z1 + p1;
;                     *(u32x4*)(mixb + (size_t)row * 1024 + col) = pack8(v0, v1); }
.LBB0_452:
	s_waitcnt vmcnt(7)
	v_lshlrev_b32_e32 v140, 16, v122
	v_and_b32_e32 v141, 0xffff0000, v122
	v_lshlrev_b32_e32 v122, 16, v123
	v_and_b32_e32 v123, 0xffff0000, v123
	v_lshlrev_b32_e32 v142, 16, v124
	v_and_b32_e32 v143, 0xffff0000, v124
	v_lshlrev_b32_e32 v124, 16, v125
	v_and_b32_e32 v125, 0xffff0000, v125
	v_lshlrev_b32_e32 v144, 16, v130
	v_and_b32_e32 v145, 0xffff0000, v130
	v_lshlrev_b32_e32 v130, 16, v131
	v_and_b32_e32 v131, 0xffff0000, v131
	v_lshlrev_b32_e32 v146, 16, v132
	v_and_b32_e32 v147, 0xffff0000, v132
	v_lshlrev_b32_e32 v132, 16, v133
	v_and_b32_e32 v133, 0xffff0000, v133
	v_pk_fma_f32 v[64:65], v[64:65], v[122:123], v[130:131]
	v_pk_fma_f32 v[62:63], v[62:63], v[140:141], v[144:145]
	v_pk_fma_f32 v[122:123], v[60:61], v[124:125], v[132:133]
	v_pk_fma_f32 v[60:61], v[58:59], v[142:143], v[146:147]
	v_cvt_pk_bf16_f32 v58, v62, v63
	v_cvt_pk_bf16_f32 v59, v64, v65
	v_cvt_pk_bf16_f32 v60, v60, v61
	v_cvt_pk_bf16_f32 v61, v122, v123
	v_lshl_add_u64 v[62:63], v[138:139], 0, v[126:127]
	global_store_dwordx4 v[62:63], v[58:61], off sc1
	s_waitcnt vmcnt(7)
	v_lshlrev_b32_e32 v64, 16, v120
	v_and_b32_e32 v65, 0xffff0000, v120
	v_lshlrev_b32_e32 v58, 16, v118
	v_and_b32_e32 v59, 0xffff0000, v118
	v_lshlrev_b32_e32 v60, 16, v119
	v_and_b32_e32 v61, 0xffff0000, v119
	v_lshlrev_b32_e32 v118, 16, v121
	v_and_b32_e32 v119, 0xffff0000, v121
	v_lshlrev_b32_e32 v120, 16, v114
	v_and_b32_e32 v121, 0xffff0000, v114
	v_lshlrev_b32_e32 v114, 16, v115
	v_and_b32_e32 v115, 0xffff0000, v115
	v_lshlrev_b32_e32 v122, 16, v116
	v_and_b32_e32 v123, 0xffff0000, v116
	v_lshlrev_b32_e32 v116, 16, v117
	v_and_b32_e32 v117, 0xffff0000, v117
	v_pk_fma_f32 v[56:57], v[56:57], v[60:61], v[114:115]
	v_pk_fma_f32 v[54:55], v[54:55], v[58:59], v[120:121]
	v_pk_fma_f32 v[58:59], v[52:53], v[118:119], v[116:117]
	v_pk_fma_f32 v[52:53], v[50:51], v[64:65], v[122:123]
	v_cvt_pk_bf16_f32 v50, v54, v55
	v_cvt_pk_bf16_f32 v51, v56, v57
	v_cvt_pk_bf16_f32 v52, v52, v53
	v_cvt_pk_bf16_f32 v53, v58, v59
	global_store_dwordx4 v[62:63], v[50:53], off offset:256 sc1
	s_waitcnt vmcnt(7)
	v_lshlrev_b32_e32 v54, 16, v112
	v_and_b32_e32 v55, 0xffff0000, v112
	v_lshlrev_b32_e32 v50, 16, v110
	v_and_b32_e32 v51, 0xffff0000, v110
	v_lshlrev_b32_e32 v52, 16, v111
	v_and_b32_e32 v53, 0xffff0000, v111
	v_lshlrev_b32_e32 v56, 16, v113
	v_and_b32_e32 v57, 0xffff0000, v113
	v_lshlrev_b32_e32 v58, 16, v98
	v_and_b32_e32 v59, 0xffff0000, v98
	v_lshlrev_b32_e32 v60, 16, v99
	v_and_b32_e32 v61, 0xffff0000, v99
	v_lshlrev_b32_e32 v62, 16, v100
	v_and_b32_e32 v63, 0xffff0000, v100
	v_lshlrev_b32_e32 v64, 16, v101
	v_and_b32_e32 v65, 0xffff0000, v101
	v_pk_fma_f32 v[48:49], v[48:49], v[52:53], v[60:61]
	v_pk_fma_f32 v[46:47], v[46:47], v[50:51], v[58:59]
	v_pk_fma_f32 v[50:51], v[44:45], v[56:57], v[64:65]
	v_pk_fma_f32 v[44:45], v[42:43], v[54:55], v[62:63]
	v_cvt_pk_bf16_f32 v42, v46, v47
	v_cvt_pk_bf16_f32 v43, v48, v49
	v_cvt_pk_bf16_f32 v44, v44, v45
	v_cvt_pk_bf16_f32 v45, v50, v51
	v_lshl_add_u64 v[46:47], v[136:137], 0, v[126:127]
	global_store_dwordx4 v[46:47], v[42:45], off sc1
	s_waitcnt vmcnt(7)
	v_lshlrev_b32_e32 v48, 16, v108
	v_and_b32_e32 v49, 0xffff0000, v108
	v_lshlrev_b32_e32 v42, 16, v106
	v_and_b32_e32 v43, 0xffff0000, v106
	v_lshlrev_b32_e32 v44, 16, v107
	v_and_b32_e32 v45, 0xffff0000, v107
	v_lshlrev_b32_e32 v50, 16, v109
	v_and_b32_e32 v51, 0xffff0000, v109
	v_lshlrev_b32_e32 v52, 16, v102
	v_and_b32_e32 v53, 0xffff0000, v102
	v_lshlrev_b32_e32 v54, 16, v103
	v_and_b32_e32 v55, 0xffff0000, v103
	v_lshlrev_b32_e32 v56, 16, v104
	v_and_b32_e32 v57, 0xffff0000, v104
	v_lshlrev_b32_e32 v58, 16, v105
	v_and_b32_e32 v59, 0xffff0000, v105
	v_pk_fma_f32 v[40:41], v[40:41], v[44:45], v[54:55]
	v_pk_fma_f32 v[38:39], v[38:39], v[42:43], v[52:53]
	v_pk_fma_f32 v[42:43], v[36:37], v[50:51], v[58:59]
	v_pk_fma_f32 v[36:37], v[34:35], v[48:49], v[56:57]
	v_cvt_pk_bf16_f32 v34, v38, v39
	v_cvt_pk_bf16_f32 v35, v40, v41
	v_cvt_pk_bf16_f32 v36, v36, v37
	v_cvt_pk_bf16_f32 v37, v42, v43
	global_store_dwordx4 v[46:47], v[34:37], off offset:256 sc1
	s_waitcnt vmcnt(7)
; DI u32x4 pack8(f32x4 a, f32x4 b) { u32x4 w; w.x = cvt_pk_bf16(a[0], a[1]); w.y = cvt_pk_bf16(a[2], a[3]); w.z = cvt_pk_bf16(b[0], b[1]); w.w = cvt_pk_bf16(b[2], b[3]); return w; }
; template <class Epi, class Sched, bool ALIGN_EPI = false, bool SP2 = false>
; __device__ __forceinline__ void gemm_phase(const int tid, PG8_LAS unsigned char* lds, const Gemm g, const Sched& S, const Epi& E) {
;     ...
;         if constexpr (!Epi::AFTER_DRAIN) { E(acc, cur, wr, wc, fr, fq); S.done(cur); }
;     DI void operator()(const f32x4 (&acc)[2][2][4][2], const Unit& u, int wr, int wc, int fr, int fq) const {
;     ...
;             for (int m = 0; m < 4; ++m)
; #pragma unroll
;                 for (int bj = 0; bj < 2; ++bj) { const int row = rowb + ai * 128 + m * 16, col = colb + bj * 128;
;                     f32x4 z0, z1, p0, p1; unpack8(zr[m][bj], z0, z1); unpack8(mr[m][bj], p0, p1);
;                     const f32x4 v0 = acc[ai][bj][m][0] * z0 + p0, v1 = acc[ai][bj][m][1] * z1 + p1;
;                     *(u32x4*)(mixb + (size_t)row * 1024 + col) = pack8(v0, v1); }
	v_lshlrev_b32_e32 v38, 16, v96
	v_and_b32_e32 v39, 0xffff0000, v96
	v_lshlrev_b32_e32 v34, 16, v94
	v_and_b32_e32 v35, 0xffff0000, v94
	v_lshlrev_b32_e32 v36, 16, v95
	v_and_b32_e32 v37, 0xffff0000, v95
	v_lshlrev_b32_e32 v40, 16, v97
	v_and_b32_e32 v41, 0xffff0000, v97
	v_lshlrev_b32_e32 v42, 16, v82
	v_and_b32_e32 v43, 0xffff0000, v82
	v_lshlrev_b32_e32 v44, 16, v83
	v_and_b32_e32 v45, 0xffff0000, v83
	v_lshlrev_b32_e32 v46, 16, v84
	v_and_b32_e32 v47, 0xffff0000, v84
	v_lshlrev_b32_e32 v48, 16, v85
	v_and_b32_e32 v49, 0xffff0000, v85
	v_pk_fma_f32 v[30:31], v[30:31], v[36:37], v[44:45]
	v_pk_fma_f32 v[28:29], v[28:29], v[34:35], v[42:43]
	v_pk_fma_f32 v[34:35], v[26:27], v[40:41], v[48:49]
	v_pk_fma_f32 v[26:27], v[24:25], v[38:39], v[46:47]
	v_cvt_pk_bf16_f32 v24, v28, v29
	v_cvt_pk_bf16_f32 v25, v30, v31
	v_cvt_pk_bf16_f32 v26, v26, v27
	v_cvt_pk_bf16_f32 v27, v34, v35
	v_lshl_add_u64 v[28:29], v[134:135], 0, v[126:127]
	global_store_dwordx4 v[28:29], v[24:27], off sc1
	s_waitcnt vmcnt(7)
	v_lshlrev_b32_e32 v30, 16, v92
	v_and_b32_e32 v31, 0xffff0000, v92
	v_lshlrev_b32_e32 v24, 16, v90
	v_and_b32_e32 v25, 0xffff0000, v90
	v_lshlrev_b32_e32 v26, 16, v91
	v_and_b32_e32 v27, 0xffff0000, v91
	v_lshlrev_b32_e32 v34, 16, v93
	v_and_b32_e32 v35, 0xffff0000, v93
	v_lshlrev_b32_e32 v36, 16, v86
	v_and_b32_e32 v37, 0xffff0000, v86
	v_lshlrev_b32_e32 v38, 16, v87
	v_and_b32_e32 v39, 0xffff0000, v87
	v_lshlrev_b32_e32 v40, 16, v88
	v_and_b32_e32 v41, 0xffff0000, v88
	v_lshlrev_b32_e32 v42, 16, v89
	v_and_b32_e32 v43, 0xffff0000, v89
	v_pk_fma_f32 v[22:23], v[22:23], v[26:27], v[38:39]
	v_pk_fma_f32 v[20:21], v[20:21], v[24:25], v[36:37]
	v_pk_fma_f32 v[24:25], v[18:19], v[34:35], v[42:43]
	v_pk_fma_f32 v[18:19], v[16:17], v[30:31], v[40:41]
	v_cvt_pk_bf16_f32 v16, v20, v21
	v_cvt_pk_bf16_f32 v17, v22, v23
	v_cvt_pk_bf16_f32 v18, v18, v19
	v_cvt_pk_bf16_f32 v19, v24, v25
	global_store_dwordx4 v[28:29], v[16:19], off offset:256 sc1
	s_waitcnt vmcnt(7)
	v_lshlrev_b32_e32 v20, 16, v80
	v_and_b32_e32 v21, 0xffff0000, v80
	v_lshlrev_b32_e32 v16, 16, v78
	v_and_b32_e32 v17, 0xffff0000, v78
	v_lshlrev_b32_e32 v18, 16, v79
	v_and_b32_e32 v19, 0xffff0000, v79
	v_lshlrev_b32_e32 v22, 16, v81
	v_and_b32_e32 v23, 0xffff0000, v81
	v_lshlrev_b32_e32 v24, 16, v66
	v_and_b32_e32 v25, 0xffff0000, v66
	v_lshlrev_b32_e32 v26, 16, v67
	v_and_b32_e32 v27, 0xffff0000, v67
	v_lshlrev_b32_e32 v28, 16, v68
	v_and_b32_e32 v29, 0xffff0000, v68
	v_lshlrev_b32_e32 v30, 16, v69
	v_and_b32_e32 v31, 0xffff0000, v69
	v_pk_fma_f32 v[14:15], v[14:15], v[18:19], v[26:27]
	v_pk_fma_f32 v[12:13], v[12:13], v[16:17], v[24:25]
	v_pk_fma_f32 v[16:17], v[10:11], v[22:23], v[30:31]
	v_pk_fma_f32 v[10:11], v[8:9], v[20:21], v[28:29]
	v_cvt_pk_bf16_f32 v8, v12, v13
	v_cvt_pk_bf16_f32 v9, v14, v15
	v_cvt_pk_bf16_f32 v10, v10, v11
	v_cvt_pk_bf16_f32 v11, v16, v17
	v_lshl_add_u64 v[12:13], v[128:129], 0, v[126:127]
	global_store_dwordx4 v[12:13], v[8:11], off sc1
	s_waitcnt vmcnt(7)
	v_lshlrev_b32_e32 v14, 16, v76
	v_and_b32_e32 v15, 0xffff0000, v76
	v_lshlrev_b32_e32 v8, 16, v74
	v_and_b32_e32 v9, 0xffff0000, v74
	v_lshlrev_b32_e32 v10, 16, v75
	v_and_b32_e32 v11, 0xffff0000, v75
	v_lshlrev_b32_e32 v16, 16, v77
	v_and_b32_e32 v17, 0xffff0000, v77
	v_lshlrev_b32_e32 v18, 16, v70
	v_and_b32_e32 v19, 0xffff0000, v70
	v_lshlrev_b32_e32 v20, 16, v71
	v_and_b32_e32 v21, 0xffff0000, v71
	v_lshlrev_b32_e32 v22, 16, v72
	v_and_b32_e32 v23, 0xffff0000, v72
	v_lshlrev_b32_e32 v24, 16, v73
	v_and_b32_e32 v25, 0xffff0000, v73
	v_pk_fma_f32 v[6:7], v[6:7], v[10:11], v[20:21]
	v_pk_fma_f32 v[4:5], v[4:5], v[8:9], v[18:19]
	v_pk_fma_f32 v[8:9], v[2:3], v[16:17], v[24:25]
	v_pk_fma_f32 v[2:3], v[0:1], v[14:15], v[22:23]
	v_cvt_pk_bf16_f32 v0, v4, v5
	v_cvt_pk_bf16_f32 v1, v6, v7
	v_cvt_pk_bf16_f32 v2, v2, v3
	v_cvt_pk_bf16_f32 v3, v8, v9
	s_andn2_b64 vcc, exec, s[4:5]
	s_mov_b64 s[4:5], -1
	global_store_dwordx4 v[12:13], v[0:3], off offset:256 sc1
	s_cmp_eq_u32 s66, 2
	s_cbranch_scc1 .Lbr_noflag
	s_waitcnt vmcnt(0)
	s_mov_b64 exec, 1
	global_atomic_add v33, v231, s[100:101]
	s_mov_b64 exec, -1
.Lbr_noflag:
	s_cbranch_vccnz .LBB0_407
	s_andn2_b64 vcc, exec, s[16:17]
	s_cbranch_vccnz .LBB0_406
	s_barrier
	s_branch .LBB0_406
